# v27 + group 0 as well: 128 early units (column tiles 6..9) on workgroups 140..255 during the branch-projection phase, the following phase enumerates the remaining 768
# speedup vs baseline: 1.0275x; 1.0074x over previous
; #define TIDV tid_opaque()
; #define BIDX bid_opaque()
; #define GDIM gdim_opaque()
; template <int KIND> DI void run_phase(PARAMS P, int l, int g) {
;     ...
;     else if constexpr (KIND == 7) {
;         { pg8::Gemm gm{(const bf16_t*)((unsigned char*)P.out + DS_MIXB), wl + WL_WOUT, gr, D, D}; pg8::StaticOrder S; S.init(gr, D, GDIM, (BIDX + GDIM / 2) % GDIM);
;           EpiRes E{X + (size_t)gbs * D}; pg8::gemm_phase<EpiRes, pg8::StaticOrder, true, true>(TIDV, lds, gm, S, E); }
;         if (g < NGROUP - 1) { const int g2 = g + 1, gr2 = grows(g2), gbs2 = gbase(g2);
;           pg8::Gemm gm{XN + (size_t)gbs2 * D, wl + WL_WIN, gr2, NIN, D}; pg8::StaticOrder S; S.init(gr2, NIN, GDIM, BIDX);
;           EpiIn E{gb, (const float*)(P.ws + WS_ROT), g2}; pg8::gemm_phase<EpiIn, pg8::StaticOrder, true, true>(TIDV, lds, gm, S, E); }
.Lk7_entry:
	s_mov_b32 s98, 0
	s_cmp_lg_u32 s92, 0x100
	s_cbranch_scc1 .Lk7_mode_done
	s_cmp_gt_u32 s34, 2
	s_cbranch_scc1 .Lk7_mode_done
	s_cmp_eq_u32 s34, 0
	s_cbranch_scc1 .Lk7_mode_g0
	s_mov_b32 s98, 1
	s_mov_b32 s99, 0x080a0280
	s_cmp_eq_u32 s31, 6
	s_cbranch_scc0 .Lk7_mode_done
	s_mov_b32 s98, 2
	s_mov_b32 s99, 0x01000080
	s_branch .Lk7_mode_done
.Lk7_mode_g0:
	s_mov_b32 s98, 1
	s_mov_b32 s99, 0x040c0300
	s_cmp_eq_u32 s31, 6
	s_cbranch_scc0 .Lk7_mode_done
	s_mov_b32 s98, 2
	s_mov_b32 s99, 0x0080008c

;     DI bool next(int i, Unit& u) const { if (!S.next(i / 3, u)) return false; const int z = i % 3; u.z = z; u.offA = (unsigned)z * (unsigned)(G0ROWS * 512 * 2); u.offB = (unsigned)z * (unsigned)(524288 * 2); return true; }
;     DI bool next(int i, Unit& u) const { const int j = i * G + c; if (j >= 3 * 4 * NKSL) return false; u.pm = MMAIN / 256 + j / (4 * NKSL); u.pn = (j / NKSL) & 3; const int kh = j % NKSL; u.z = kh; u.offA = (unsigned)(kh * 512); u.offB = (unsigned)(kh * 512); return true; }
;     __host__ __device__ bool next(int i, Unit& u) const {
;         const long L = (long)i * G + c; if (L >= nwg) return false;
;         int wgid = (int)L; { const int q = nwg / NXCD, r = nwg % NXCD, xcd = wgid % NXCD, off = wgid / NXCD; wgid = (xcd < r ? xcd * (q + 1) : r * (q + 1) + (xcd - r) * q) + off; }
;         const int nig = WGM * nN, gid = wgid / nig, fm = gid * WGM, gsz = (nM - fm) < WGM ? (nM - fm) : WGM;
;         u.pm = fm + ((wgid % nig) % gsz); u.pn = (wgid % nig) / gsz; return true;
.LBB0_234:
	s_cmp_eq_u32 s98, 0
	s_cbranch_scc1 .Lgi_a_done
	s_cmp_eq_u32 s98, 2
	s_cbranch_scc1 .Lgi_a_early
	s_mov_b32 s2, s79
	s_and_b32 s3, s99, 0xffff
	s_cmp_lt_u32 s2, s3
	s_cselect_b64 s[16:17], -1, 0
	s_and_b32 s3, s2, 7
	s_lshr_b32 s2, s2, 3
	s_lshr_b32 s5, s3, 1
	s_lshl_b32 s5, s5, 3
	s_and_b32 s10, s2, 7
	s_add_i32 s4, s5, s10
	s_and_b32 s3, s3, 1
	s_bfe_u32 s5, s99, 0x80010
	s_mul_i32 s3, s3, s5
	s_lshr_b32 s2, s2, 3
	s_add_i32 s40, s3, s2
	s_cmp_lt_u32 s40, 6
	s_cbranch_scc1 .Lgi_a_done
	s_lshr_b32 s2, s99, 24
	s_add_i32 s40, s40, s2
	s_branch .Lgi_a_done
.Lgi_a_early:
	s_and_b32 s3, s99, 0xffff
	s_sub_i32 s2, s79, s3
	s_lshr_b32 s3, s99, 16
	s_cmp_lt_u32 s2, s3
	s_cselect_b64 s[16:17], -1, 0
	s_and_b32 s3, s2, 7
	s_lshr_b32 s2, s2, 3
	s_lshl_b32 s3, s3, 2
	s_and_b32 s5, s2, 3
	s_add_i32 s4, s3, s5
	s_lshr_b32 s2, s2, 2
	s_add_i32 s40, s2, 6

;     DI bool next(int i, Unit& u) const { if (!S.next(i / 3, u)) return false; const int z = i % 3; u.z = z; u.offA = (unsigned)z * (unsigned)(G0ROWS * 512 * 2); u.offB = (unsigned)z * (unsigned)(524288 * 2); return true; }
;     DI bool next(int i, Unit& u) const { const int j = i * G + c; if (j >= 3 * 4 * NKSL) return false; u.pm = MMAIN / 256 + j / (4 * NKSL); u.pn = (j / NKSL) & 3; const int kh = j % NKSL; u.z = kh; u.offA = (unsigned)(kh * 512); u.offB = (unsigned)(kh * 512); return true; }
;     __host__ __device__ bool next(int i, Unit& u) const {
;         const long L = (long)i * G + c; if (L >= nwg) return false;
;         int wgid = (int)L; { const int q = nwg / NXCD, r = nwg % NXCD, xcd = wgid % NXCD, off = wgid / NXCD; wgid = (xcd < r ? xcd * (q + 1) : r * (q + 1) + (xcd - r) * q) + off; }
;         const int nig = WGM * nN, gid = wgid / nig, fm = gid * WGM, gsz = (nM - fm) < WGM ? (nM - fm) : WGM;
;         u.pm = fm + ((wgid % nig) % gsz); u.pn = (wgid % nig) / gsz; return true;
.LBB0_240:
	s_add_i32 s36, s36, 1
	s_cmp_eq_u32 s98, 0
	s_cbranch_scc1 .Lgi_b_orig
	s_cmp_eq_u32 s98, 2
	s_cbranch_scc1 .Lgi_b_early
	s_mul_i32 s0, s36, s78
	s_add_i32 s0, s0, s79
	s_and_b32 s1, s99, 0xffff
	s_cmp_lt_u32 s0, s1
	s_cselect_b64 s[38:39], -1, 0
	s_cbranch_scc0 .Lgi_b_done
	s_and_b32 s1, s0, 7
	s_lshr_b32 s0, s0, 3
	s_lshr_b32 s2, s1, 1
	s_lshl_b32 s2, s2, 3
	s_and_b32 s3, s0, 7
	s_add_i32 s56, s2, s3
	s_and_b32 s1, s1, 1
	s_bfe_u32 s2, s99, 0x80010
	s_mul_i32 s1, s1, s2
	s_lshr_b32 s0, s0, 3
	s_add_i32 s54, s1, s0
	s_cmp_lt_u32 s54, 6
	s_cbranch_scc1 .Lgi_b_done
	s_lshr_b32 s0, s99, 24
	s_add_i32 s54, s54, s0
	s_branch .Lgi_b_done
.Lgi_b_early:
	s_and_b32 s1, s99, 0xffff
	s_sub_i32 s0, s78, s1
	s_mul_i32 s0, s0, s36
	s_add_i32 s0, s0, s79
	s_sub_i32 s0, s0, s1
	s_lshr_b32 s1, s99, 16
	s_cmp_lt_u32 s0, s1
	s_cselect_b64 s[38:39], -1, 0
	s_cbranch_scc0 .Lgi_b_done
	s_and_b32 s1, s0, 7
	s_lshr_b32 s0, s0, 3
	s_lshl_b32 s1, s1, 2
	s_and_b32 s2, s0, 3
	s_add_i32 s56, s1, s2
	s_lshr_b32 s0, s0, 2
	s_add_i32 s54, s0, 6

; #define TIDV tid_opaque()
; #define BIDX bid_opaque()
; #define GDIM gdim_opaque()
; template <int KIND> DI void run_phase(PARAMS P, int l, int g) {
;     ...
;     else if constexpr (KIND == 6) {
;         pg8::Gemm gm{(const bf16_t*)((unsigned char*)P.out + DS_OB), wl + WL_WBR, gr, D, 512};
;         BrOrder S; S.S.init(gr, D, GDIM, BIDX);
;         EpiBr E{gb + (size_t)CP_ZG * G0ROWS, (float*)((unsigned char*)P.out + DS_MIXF), (bf16_t*)((unsigned char*)P.out + DS_MIXB)};
;         pg8::gemm_phase<EpiBr, BrOrder, true, true>(TIDV, lds, gm, S, E); }
.LBB0_395:
	s_and_b64 vcc, exec, s[4:5]
	s_cbranch_vccz .LBB0_456
	s_cmp_lg_u32 s92, 0x100
	s_cbranch_scc1 .Lk6_normal
	s_cmp_gt_u32 s34, 2
	s_cbranch_scc1 .Lk6_normal
	s_movk_i32 s99, 0x80
	s_cmp_eq_u32 s34, 0
	s_cselect_b32 s99, 0x8c, s99
	s_cmp_lt_u32 s82, s99
	s_cbranch_scc1 .Lk6_normal
	s_branch .Lk7_entry
